# in-proj epilogue: sh/gn vector loads issued together instead of 4-8 serialized load+vmcnt(0) round trips (on top of scan rewrite)
# baseline (speedup 1.0000x reference)
; #define GAS __attribute__((address_space(1)))
;     __device__ __forceinline__ void operator()(const f32x4 (&acc)[2][2][4][2], const pg8::Unit& u, int wr, int wc, int fr, int fq) const {
;         const int slot = 4 * u.pn + wc;
;         if (slot >= 46) return;
;         int type = 2;
;         if (slot < 6) type = 0; else if (slot < 12) type = 1; else if (slot < 24) type = 2; else if (slot < 30) type = 3; else if (slot < 32) type = 4;
;         const bool do_rope = type != 2, do_norm = type >= 3;
;         const float oscale = (type == 1 || type == 3) ? 0.125f : 1.0f;
;         const GAS float* gain = (type == 3) ? qn : kn;
;         f32x4 sh[2][2], gn[2][2];
; #pragma unroll
;         for (int bj = 0; bj < 2; ++bj)
; #pragma unroll
;             for (int n = 0; n < 2; ++n) {
;                 sh[bj][n] = *(const GAS f32x4*)(shW + 256 * u.pn + 128 * bj + 32 * wc + 8 * fq + 4 * n);
;                 gn[bj][n] = do_norm ? *(const GAS f32x4*)(gain + 32 * bj + 8 * fq + 4 * n) : (f32x4){1.f, 1.f, 1.f, 1.f};
;                 if (do_norm) gn[bj][n] = gn[bj][n] * oscale; else sh[bj][n] = sh[bj][n] * oscale;
;             }
.LBB0_564:
	s_or_b64 vcc, s[54:55], s[56:57]
	v_readlane_b32 s36, v254, 15
	s_and_b64 s[54:55], s[56:57], exec
	v_readlane_b32 s38, v254, 17
	v_readlane_b32 s37, v254, 16
	v_readlane_b32 s39, v254, 18
	s_cselect_b32 s5, s36, s38
	s_cselect_b32 s3, s37, s39
	s_add_u32 s54, s5, s12
	s_addc_u32 s55, s3, s13
	s_lshl_b32 s2, s2, 8
	s_ashr_i32 s3, s2, 31
	v_lshl_add_u64 v[82:83], s[2:3], 2, v[194:195]
	global_load_dwordx4 v[66:69], v[82:83], off
	global_load_dwordx4 v[70:73], v[82:83], off offset:16
	global_load_dwordx4 v[74:77], v[82:83], off offset:512
	global_load_dwordx4 v[78:81], v[82:83], off offset:528
	v_mov_b32_e32 v88, 0x3e000000
	v_cndmask_b32_e32 v208, 1.0, v88, vcc
	v_lshlrev_b32_e32 v178, 2, v184
	v_readlane_b32 s36, v254, 31
	v_readlane_b32 s37, v254, 32
	v_readlane_b32 s38, v254, 33
	v_readlane_b32 s39, v254, 34
	v_readlane_b32 s40, v254, 35
	v_readlane_b32 s41, v254, 36
	v_readlane_b32 s42, v254, 37
	v_readlane_b32 s43, v254, 38
	v_readlane_b32 s44, v254, 39
	v_readlane_b32 s45, v254, 40
	v_readlane_b32 s46, v254, 41
	v_readlane_b32 s47, v254, 42
	v_readlane_b32 s48, v254, 43
	v_readlane_b32 s49, v254, 44
	v_readlane_b32 s50, v254, 45
	v_readlane_b32 s51, v254, 46
	v_lshl_add_u64 v[86:87], s[54:55], 0, v[178:179]
	s_and_b64 vcc, exec, s[26:27]
	s_cbranch_vccnz .Lprojepi_gn
	v_mov_b32_e32 v202, 1.0
	v_mov_b32_e32 v203, 1.0
	v_mov_b32_e32 v204, 1.0
	v_mov_b32_e32 v205, 1.0
	v_mov_b32_e32 v206, 1.0
	v_mov_b32_e32 v207, 1.0
	v_mov_b32_e32 v210, 1.0
	v_mov_b32_e32 v211, 1.0
	v_mov_b32_e32 v212, 1.0
	v_mov_b32_e32 v213, 1.0
	v_mov_b32_e32 v214, 1.0
	v_mov_b32_e32 v215, 1.0
	v_mov_b32_e32 v216, 1.0
	v_mov_b32_e32 v217, 1.0
	v_mov_b32_e32 v218, 1.0
	v_mov_b32_e32 v219, 1.0
	s_branch .LBB0_581
.Lprojepi_gn:
	global_load_dwordx4 v[202:205], v[86:87], off
	global_load_dwordx2 v[206:207], v[86:87], off offset:16
	global_load_dwordx2 v[210:211], v[86:87], off offset:24
	global_load_dwordx4 v[212:215], v[86:87], off offset:128
	global_load_dwordx4 v[216:219], v[86:87], off offset:144

; #define GAS __attribute__((address_space(1)))
;     __device__ __forceinline__ void operator()(const f32x4 (&acc)[2][2][4][2], const pg8::Unit& u, int wr, int wc, int fr, int fq) const {
;     ...
;                 sh[bj][n] = *(const GAS f32x4*)(shW + 256 * u.pn + 128 * bj + 32 * wc + 8 * fq + 4 * n);
;                 gn[bj][n] = do_norm ? *(const GAS f32x4*)(gain + 32 * bj + 8 * fq + 4 * n) : (f32x4){1.f, 1.f, 1.f, 1.f};
;                 if (do_norm) gn[bj][n] = gn[bj][n] * oscale; else sh[bj][n] = sh[bj][n] * oscale;
;             }
;         const int row0 = 256 * u.pm + 64 * wr + fr;
;         float rs[2][4];
; #pragma unroll
;         for (int ai = 0; ai < 2; ++ai)
; #pragma unroll
;             for (int m = 0; m < 4; ++m) rs[ai][m] = (float)ssq[row0 + 128 * ai + 16 * m] * (1.0f / 1024.0f);
; #pragma unroll
;         for (int ai = 0; ai < 2; ++ai) {
;             u32x4 cs[4][2];
;             if (do_rope) {
; #pragma unroll
;                 for (int m = 0; m < 4; ++m)
; #pragma unroll
;                     for (int n = 0; n < 2; ++n) cs[m][n] = *(const GAS u32x4*)(csT + (size_t)(row0 + 128 * ai + 16 * m) * 32 + 8 * fq + 4 * n);
;             }
; #pragma unroll
;             for (int m = 0; m < 4; ++m) {
;                 {
;                     const int row = row0 + 128 * ai + 16 * m;
;                     const float rstd = __builtin_amdgcn_rsqf(rs[ai][m] * (1.0f / DM) + EPSF) * (do_norm ? 1.0f : oscale);
;                     f32x4 v[2][2];
; #pragma unroll
;                     for (int bj = 0; bj < 2; ++bj)
; #pragma unroll
;                         for (int n = 0; n < 2; ++n) v[bj][n] = acc[ai][bj][m][n] * rstd + sh[bj][n];
;                     if (do_norm) {
;                         float s = 0.f;
; #pragma unroll
;                         for (int bj = 0; bj < 2; ++bj)
; #pragma unroll
;                             for (int n = 0; n < 2; ++n) { const f32x4 x = v[bj][n]; s += (x[0] * x[0] + x[1] * x[1]) + (x[2] * x[2] + x[3] * x[3]); }
;                         s += __shfl_xor(s, 16); s += __shfl_xor(s, 32);
;                         const float r = __builtin_amdgcn_rsqf(s * (1.0f / 64.0f) + EPSF);
; #pragma unroll
;                         for (int bj = 0; bj < 2; ++bj)
; #pragma unroll
;                             for (int n = 0; n < 2; ++n) v[bj][n] = v[bj][n] * r * gn[bj][n];
.LBB0_583:
	s_waitcnt vmcnt(7)
	s_and_b64 vcc, exec, s[26:27]
	s_cbranch_vccnz .Lprojepi_scale_gn
	v_mul_f32_e32 v66, v208, v66
	v_mul_f32_e32 v67, v208, v67
	v_mul_f32_e32 v68, v208, v68
	v_mul_f32_e32 v69, v208, v69
	v_mul_f32_e32 v70, v208, v70
	v_mul_f32_e32 v71, v208, v71
	v_mul_f32_e32 v72, v208, v72
	v_mul_f32_e32 v73, v208, v73
	v_mul_f32_e32 v74, v208, v74
	v_mul_f32_e32 v75, v208, v75
	v_mul_f32_e32 v76, v208, v76
	v_mul_f32_e32 v77, v208, v77
	v_mul_f32_e32 v78, v208, v78
	v_mul_f32_e32 v79, v208, v79
	v_mul_f32_e32 v80, v208, v80
	v_mul_f32_e32 v81, v208, v81
	s_branch .Lprojepi_scale_done
.Lprojepi_scale_gn:
	v_mul_f32_e32 v202, v208, v202
	v_mul_f32_e32 v203, v208, v203
	v_mul_f32_e32 v204, v208, v204
	v_mul_f32_e32 v205, v208, v205
	v_mul_f32_e32 v206, v208, v206
	v_mul_f32_e32 v207, v208, v207
	v_mul_f32_e32 v210, v208, v210
	v_mul_f32_e32 v211, v208, v211
	v_mul_f32_e32 v212, v208, v212
	v_mul_f32_e32 v213, v208, v213
	v_mul_f32_e32 v214, v208, v214
	v_mul_f32_e32 v215, v208, v215
	v_mul_f32_e32 v216, v208, v216
	v_mul_f32_e32 v217, v208, v217
	v_mul_f32_e32 v218, v208, v218
	v_mul_f32_e32 v219, v208, v219
	v_mov_b32_e32 v208, 1.0
.Lprojepi_scale_done:
	v_cvt_f32_u32_e32 v180, v244
	s_andn2_b64 vcc, exec, s[26:27]
	v_xor_b32_e32 v244, 16, v232
	v_and_b32_e32 v245, 64, v232
	v_mul_f32_e32 v180, 0x3a800000, v180
	v_fmamk_f32 v180, v180, 0x3a800000, v233
	v_rsq_f32_e32 v180, v180
	v_xor_b32_e32 v221, 32, v232
	v_mul_f32_e32 v180, v208, v180
	v_pk_fma_f32 v[176:177], v[176:177], v[180:181], v[68:69] op_sel_hi:[1,0,1]
	v_pk_fma_f32 v[174:175], v[174:175], v[180:181], v[66:67] op_sel_hi:[1,0,1]
	v_pk_fma_f32 v[172:173], v[172:173], v[180:181], v[72:73] op_sel_hi:[1,0,1]
	v_pk_fma_f32 v[170:171], v[170:171], v[180:181], v[70:71] op_sel_hi:[1,0,1]
	v_pk_fma_f32 v[168:169], v[168:169], v[180:181], v[76:77] op_sel_hi:[1,0,1]
	v_pk_fma_f32 v[166:167], v[166:167], v[180:181], v[74:75] op_sel_hi:[1,0,1]
	v_pk_fma_f32 v[164:165], v[164:165], v[180:181], v[80:81] op_sel_hi:[1,0,1]
	v_pk_fma_f32 v[162:163], v[162:163], v[180:181], v[78:79] op_sel_hi:[1,0,1]
	v_cndmask_b32_e64 v180, 0, 1, s[26:27]
	v_cmp_ne_u32_e64 s[4:5], 1, v180
	s_cbranch_vccnz .LBB0_585
	v_pk_mul_f32 v[180:181], v[176:177], v[176:177]
	v_pk_mul_f32 v[182:183], v[174:175], v[174:175]
	s_nop 0
	v_pk_mov_b32 v[252:253], v[182:183], v[180:181] op_sel:[1,0]
	v_mov_b32_e32 v183, v181
	v_pk_add_f32 v[180:181], v[252:253], v[182:183]
	v_pk_mul_f32 v[182:183], v[172:173], v[172:173]
	v_pk_add_f32 v[180:181], v[180:181], v[180:181] op_sel_hi:[0,1]
	v_pk_mul_f32 v[252:253], v[170:171], v[170:171]
	v_mul_f32_e32 v180, v166, v166
	v_pk_mov_b32 v[230:231], v[252:253], v[182:183] op_sel:[1,0]
	v_mov_b32_e32 v253, v183
	v_pk_add_f32 v[182:183], v[230:231], v[252:253]
	v_pk_fma_f32 v[230:231], v[166:167], v[166:167], v[180:181] op_sel_hi:[1,1,0]
	v_mul_f32_e32 v180, v168, v168
	v_pk_add_f32 v[182:183], v[182:183], v[182:183] op_sel_hi:[0,1]
	v_pk_fma_f32 v[252:253], v[168:169], v[168:169], v[180:181] op_sel_hi:[1,1,0]
	v_mul_f32_e32 v230, v162, v162
	v_mul_f32_e32 v252, v163, v163
	v_mul_f32_e32 v180, v164, v164
	v_mul_f32_e32 v182, v165, v165
	v_pk_add_f32 v[230:231], v[230:231], v[252:253]
	v_pk_add_f32 v[180:181], v[180:181], v[182:183]
	s_nop 0
	v_pk_add_f32 v[180:181], v[230:231], v[180:181]
	s_nop 0
	v_add_f32_e32 v180, v180, v181
	v_add_u32_e32 v181, 64, v245
	v_cmp_lt_i32_e32 vcc, v244, v181
	s_nop 1
	v_cndmask_b32_e32 v182, v232, v244, vcc
	v_lshlrev_b32_e32 v182, 2, v182
	ds_bpermute_b32 v182, v182, v180
	v_cmp_lt_i32_e32 vcc, v221, v181
	s_waitcnt lgkmcnt(0)
	v_add_f32_e32 v180, v180, v182
	v_cndmask_b32_e32 v181, v232, v221, vcc
	v_lshlrev_b32_e32 v181, 2, v181
	ds_bpermute_b32 v181, v181, v180
	s_waitcnt lgkmcnt(0)
	v_add_f32_e32 v180, v180, v181
	v_fmamk_f32 v180, v180, 0x3c800000, v233
	v_rsq_f32_e32 v180, v180
	s_nop 0
	v_pk_mul_f32 v[174:175], v[174:175], v[180:181] op_sel_hi:[1,0]
	v_pk_mul_f32 v[176:177], v[176:177], v[180:181] op_sel_hi:[1,0]
	v_pk_mul_f32 v[170:171], v[170:171], v[180:181] op_sel_hi:[1,0]
	v_pk_mul_f32 v[172:173], v[172:173], v[180:181] op_sel_hi:[1,0]
	v_pk_mul_f32 v[166:167], v[166:167], v[180:181] op_sel_hi:[1,0]
	v_pk_mul_f32 v[168:169], v[168:169], v[180:181] op_sel_hi:[1,0]
	v_pk_mul_f32 v[162:163], v[162:163], v[180:181] op_sel_hi:[1,0]
	v_pk_mul_f32 v[164:165], v[164:165], v[180:181] op_sel_hi:[1,0]
	v_pk_mul_f32 v[176:177], v[204:205], v[176:177]
	v_pk_mul_f32 v[174:175], v[202:203], v[174:175]
	v_pk_mul_f32 v[172:173], v[210:211], v[172:173]
	v_pk_mul_f32 v[170:171], v[206:207], v[170:171]
	v_pk_mul_f32 v[168:169], v[214:215], v[168:169]
	v_pk_mul_f32 v[166:167], v[212:213], v[166:167]
	v_pk_mul_f32 v[164:165], v[218:219], v[164:165]
	v_pk_mul_f32 v[162:163], v[216:217], v[162:163]
